# softmax exponent in NA/SWA fused: (s-mx)*log2e as one v_fmamk with a precomputed -mx*log2e (one VALU op fewer per element)
# speedup vs baseline: 1.0026x; 1.0026x over previous
.LBB0_503:
	s_or_b64 exec, exec, s[6:7]
	s_mov_b32 s0, 0xff61b1e6
	v_max3_f32 v0, v26, s0, v24
	v_max3_f32 v0, v0, v28, v25
	v_max3_f32 v0, v0, v34, v23
	v_max3_f32 v0, v0, v29, v27
	v_max3_f32 v0, v0, v32, v30
	v_max3_f32 v0, v0, v36, v35
	v_max3_f32 v0, v0, v38, v37
	v_max3_f32 v0, v0, v40, v39
	v_max3_f32 v0, v0, v42, v41
	v_max3_f32 v0, v0, v48, v43
	v_max3_f32 v0, v0, v51, v50
	v_max3_f32 v0, v0, v55, v54
	v_max3_f32 v0, v0, v61, v60
	v_max3_f32 v0, v0, v63, v62
	v_max3_f32 v0, v0, v88, v87
	v_max3_f32 v0, v0, v90, v89
	v_max3_f32 v0, v0, v92, v91
	v_max3_f32 v0, v0, v94, v93
	v_max3_f32 v0, v0, v96, v95
	v_max3_f32 v0, v0, v98, v97
	v_max3_f32 v0, v0, v100, v99
	v_max3_f32 v0, v0, v102, v101
	v_max3_f32 v0, v0, v104, v103
	v_max3_f32 v0, v0, v106, v105
	v_max3_f32 v0, v0, v108, v107
	v_max3_f32 v0, v0, v110, v109
	v_max3_f32 v0, v0, v112, v111
	v_max3_f32 v0, v0, v114, v113
	v_max3_f32 v0, v0, v116, v115
	v_max3_f32 v0, v0, v8, v9
	v_max3_f32 v0, v0, v22, v117
	v_max3_f32 v0, v0, v119, v118
	ds_bpermute_b32 v1, v76, v0
	s_mov_b32 s0, 0xa000000
	s_mov_b64 s[6:7], 0xa000400
	s_add_i32 s27, s27, 1
	s_waitcnt lgkmcnt(0)
	v_max_f32_e32 v1, v1, v1
	v_max_f32_e32 v0, v0, v1
	ds_bpermute_b32 v1, v77, v0
	s_waitcnt lgkmcnt(0)
	v_max_f32_e32 v1, v1, v1
	v_max_f32_e32 v120, v0, v1
	v_mul_f32_e32 v85, 0xbfb8aa3b, v120
	v_fmamk_f32 v1, v24, 0x3fb8aa3b, v85
	v_exp_f32_e32 v47, v1
	v_fmamk_f32 v1, v28, 0x3fb8aa3b, v85
	v_exp_f32_e32 v56, v1
	v_fmamk_f32 v1, v25, 0x3fb8aa3b, v85
	v_exp_f32_e32 v57, v1
	v_fmamk_f32 v1, v34, 0x3fb8aa3b, v85
	v_exp_f32_e32 v66, v1
	v_fmamk_f32 v1, v23, 0x3fb8aa3b, v85
	v_exp_f32_e32 v67, v1
	v_fmamk_f32 v1, v29, 0x3fb8aa3b, v85
	v_exp_f32_e32 v70, v1
	v_fmamk_f32 v1, v27, 0x3fb8aa3b, v85
	v_exp_f32_e32 v71, v1
	v_fmamk_f32 v1, v32, 0x3fb8aa3b, v85
	v_exp_f32_e32 v64, v1
	v_fmamk_f32 v1, v30, 0x3fb8aa3b, v85
	v_exp_f32_e32 v65, v1
	v_fmamk_f32 v1, v36, 0x3fb8aa3b, v85
	v_exp_f32_e32 v68, v1
	v_fmamk_f32 v1, v35, 0x3fb8aa3b, v85
	v_exp_f32_e32 v69, v1
	v_fmamk_f32 v1, v38, 0x3fb8aa3b, v85
	v_exp_f32_e32 v72, v1
	v_fmamk_f32 v1, v37, 0x3fb8aa3b, v85
	v_exp_f32_e32 v73, v1
	v_fmamk_f32 v1, v40, 0x3fb8aa3b, v85
	v_exp_f32_e32 v74, v1
	v_fmamk_f32 v1, v39, 0x3fb8aa3b, v85
	v_exp_f32_e32 v75, v1
	v_fmamk_f32 v1, v42, 0x3fb8aa3b, v85
	v_exp_f32_e32 v44, v1
	v_fmamk_f32 v1, v41, 0x3fb8aa3b, v85
	v_exp_f32_e32 v45, v1
	v_fmamk_f32 v1, v48, 0x3fb8aa3b, v85
	v_exp_f32_e32 v48, v1
	v_fmamk_f32 v1, v43, 0x3fb8aa3b, v85
	v_exp_f32_e32 v49, v1
	v_fmamk_f32 v1, v51, 0x3fb8aa3b, v85
	v_exp_f32_e32 v52, v1
	v_fmamk_f32 v1, v50, 0x3fb8aa3b, v85
	v_exp_f32_e32 v53, v1
	v_fmamk_f32 v1, v55, 0x3fb8aa3b, v85
	v_exp_f32_e32 v58, v1
	v_fmamk_f32 v1, v54, 0x3fb8aa3b, v85
	v_fmamk_f32 v0, v26, 0x3fb8aa3b, v85
	v_exp_f32_e32 v59, v1
	v_fmamk_f32 v1, v61, 0x3fb8aa3b, v85
	v_exp_f32_e32 v46, v0
	v_exp_f32_e32 v50, v1
	v_fmamk_f32 v1, v60, 0x3fb8aa3b, v85
	v_exp_f32_e32 v51, v1
	v_fmamk_f32 v1, v63, 0x3fb8aa3b, v85
	v_add_f32_e32 v0, 0, v46
	v_add_f32_e32 v0, v47, v0
	v_exp_f32_e32 v54, v1
	v_fmamk_f32 v1, v62, 0x3fb8aa3b, v85
	v_add_f32_e32 v0, v56, v0
	v_add_f32_e32 v0, v57, v0
	v_exp_f32_e32 v55, v1
	v_fmamk_f32 v1, v88, 0x3fb8aa3b, v85
	v_add_f32_e32 v0, v66, v0
	v_add_f32_e32 v0, v67, v0
	v_exp_f32_e32 v60, v1
	v_fmamk_f32 v1, v87, 0x3fb8aa3b, v85
	v_add_f32_e32 v0, v70, v0
	v_add_f32_e32 v0, v71, v0
	v_exp_f32_e32 v61, v1
	v_fmamk_f32 v1, v90, 0x3fb8aa3b, v85
	v_add_f32_e32 v0, v64, v0
	v_add_f32_e32 v0, v65, v0
	v_exp_f32_e32 v62, v1
	v_fmamk_f32 v1, v89, 0x3fb8aa3b, v85
	v_add_f32_e32 v0, v68, v0
	v_add_f32_e32 v0, v69, v0
	v_exp_f32_e32 v63, v1
	v_fmamk_f32 v1, v92, 0x3fb8aa3b, v85
	v_add_f32_e32 v0, v72, v0
	v_add_f32_e32 v0, v73, v0
	v_exp_f32_e32 v26, v1
	v_fmamk_f32 v1, v91, 0x3fb8aa3b, v85
	v_add_f32_e32 v0, v74, v0
	v_add_f32_e32 v0, v75, v0
	v_exp_f32_e32 v27, v1
	v_fmamk_f32 v1, v94, 0x3fb8aa3b, v85
	v_add_f32_e32 v0, v44, v0
	v_add_f32_e32 v0, v45, v0
	v_exp_f32_e32 v28, v1
	v_fmamk_f32 v1, v93, 0x3fb8aa3b, v85
	v_add_f32_e32 v0, v48, v0
	v_add_f32_e32 v0, v49, v0
	v_exp_f32_e32 v29, v1
	v_fmamk_f32 v1, v96, 0x3fb8aa3b, v85
	v_add_f32_e32 v0, v52, v0
	v_add_f32_e32 v0, v53, v0
	v_exp_f32_e32 v34, v1
	v_fmamk_f32 v1, v95, 0x3fb8aa3b, v85
	v_add_f32_e32 v0, v58, v0
	v_add_f32_e32 v0, v59, v0
	v_exp_f32_e32 v35, v1
	v_fmamk_f32 v1, v98, 0x3fb8aa3b, v85
	v_add_f32_e32 v0, v50, v0
	v_add_f32_e32 v0, v51, v0
	v_exp_f32_e32 v38, v1
	v_fmamk_f32 v1, v97, 0x3fb8aa3b, v85
	v_add_f32_e32 v0, v54, v0
	v_add_f32_e32 v0, v55, v0
	v_exp_f32_e32 v39, v1
	v_fmamk_f32 v1, v100, 0x3fb8aa3b, v85
	v_add_f32_e32 v0, v60, v0
	v_add_f32_e32 v0, v61, v0
	v_exp_f32_e32 v32, v1
	v_fmamk_f32 v1, v99, 0x3fb8aa3b, v85
	v_add_f32_e32 v0, v62, v0
	v_add_f32_e32 v0, v63, v0
	v_exp_f32_e32 v33, v1
	v_fmamk_f32 v1, v102, 0x3fb8aa3b, v85
	v_add_f32_e32 v0, v26, v0
	v_add_f32_e32 v0, v27, v0
	v_exp_f32_e32 v36, v1
	v_fmamk_f32 v1, v101, 0x3fb8aa3b, v85
	v_add_f32_e32 v0, v28, v0
	v_add_f32_e32 v0, v29, v0
	v_exp_f32_e32 v37, v1
	v_fmamk_f32 v1, v104, 0x3fb8aa3b, v85
	v_add_f32_e32 v0, v34, v0
	v_add_f32_e32 v0, v35, v0
	v_exp_f32_e32 v40, v1
	v_fmamk_f32 v1, v103, 0x3fb8aa3b, v85
	v_add_f32_e32 v0, v38, v0
	v_add_f32_e32 v0, v39, v0
	v_exp_f32_e32 v41, v1
	v_fmamk_f32 v1, v106, 0x3fb8aa3b, v85
	v_add_f32_e32 v0, v32, v0
	v_add_f32_e32 v0, v33, v0
	v_exp_f32_e32 v42, v1
	v_fmamk_f32 v1, v105, 0x3fb8aa3b, v85
	v_add_f32_e32 v0, v36, v0
	v_add_f32_e32 v0, v37, v0
	v_exp_f32_e32 v43, v1
	v_add_f32_e32 v0, v40, v0
	v_add_f32_e32 v0, v41, v0
	v_add_f32_e32 v0, v42, v0
	v_add_f32_e32 v1, v43, v0
	v_fmamk_f32 v0, v108, 0x3fb8aa3b, v85
	v_exp_f32_e32 v0, v0
	v_fmamk_f32 v5, v112, 0x3fb8aa3b, v85
	v_exp_f32_e32 v6, v5
	v_add_f32_e32 v2, v0, v1
	v_fmamk_f32 v1, v107, 0x3fb8aa3b, v85
	v_exp_f32_e32 v1, v1
	v_fmamk_f32 v5, v111, 0x3fb8aa3b, v85
	v_exp_f32_e32 v7, v5
	v_add_f32_e32 v3, v1, v2
	v_fmamk_f32 v2, v110, 0x3fb8aa3b, v85
	v_exp_f32_e32 v2, v2
	v_fmamk_f32 v5, v114, 0x3fb8aa3b, v85
	v_exp_f32_e32 v10, v5
	v_add_f32_e32 v4, v2, v3
	v_fmamk_f32 v3, v109, 0x3fb8aa3b, v85
	v_exp_f32_e32 v3, v3
	v_fmamk_f32 v5, v113, 0x3fb8aa3b, v85
	v_exp_f32_e32 v11, v5
	v_add_f32_e32 v4, v3, v4
	v_add_f32_e32 v4, v6, v4
	v_add_f32_e32 v4, v7, v4
	v_add_f32_e32 v4, v10, v4
	v_add_f32_e32 v5, v11, v4
	v_fmamk_f32 v4, v116, 0x3fb8aa3b, v85
	v_exp_f32_e32 v4, v4
	v_sub_f32_e32 v8, v8, v120
	v_mul_f32_e32 v8, 0x3fb8aa3b, v8
	v_sub_f32_e32 v9, v9, v120
	v_add_f32_e32 v23, v4, v5
	v_fmamk_f32 v5, v115, 0x3fb8aa3b, v85
	v_exp_f32_e32 v5, v5
	v_exp_f32_e32 v8, v8
	v_mul_f32_e32 v9, 0x3fb8aa3b, v9
	v_sub_f32_e32 v22, v22, v120
	v_exp_f32_e32 v9, v9
	v_mul_f32_e32 v22, 0x3fb8aa3b, v22
	v_exp_f32_e32 v22, v22
	v_add_f32_e32 v23, v5, v23
	v_add_f32_e32 v23, v8, v23
	v_add_f32_e32 v23, v9, v23
	v_add_f32_e32 v24, v22, v23
	v_fmamk_f32 v23, v117, 0x3fb8aa3b, v85
	v_exp_f32_e32 v23, v23
	s_nop 0
	v_add_f32_e32 v25, v23, v24
	v_fmamk_f32 v24, v119, 0x3fb8aa3b, v85
	v_exp_f32_e32 v24, v24
	s_nop 0
	v_add_f32_e32 v30, v24, v25
	v_fmamk_f32 v25, v118, 0x3fb8aa3b, v85
	v_exp_f32_e32 v25, v25
	s_nop 0
	v_add_f32_e32 v30, v25, v30
	ds_bpermute_b32 v87, v76, v30
	s_waitcnt lgkmcnt(0)
	v_add_f32_e32 v30, v30, v87
	ds_bpermute_b32 v87, v77, v30
	s_waitcnt lgkmcnt(0)
	v_add_f32_e32 v30, v30, v87
	v_rcp_f32_e32 v30, v30
	v_lshl_add_u32 v87, v86, 1, v78
	ds_read_b128 v[92:95], v87 offset:65280
	v_add_u32_e32 v86, 0xff00, v87
	v_pk_mul_f32 v[56:57], v[56:57], v[30:31] op_sel_hi:[1,0]
	v_pk_mul_f32 v[46:47], v[46:47], v[30:31] op_sel_hi:[1,0]
	v_cvt_pk_bf16_f32 v89, v56, v57
	v_pk_mul_f32 v[56:57], v[70:71], v[30:31] op_sel_hi:[1,0]
	ds_read_b128 v[96:99], v86 offset:15616
	v_cvt_pk_bf16_f32 v91, v56, v57
	v_pk_mul_f32 v[56:57], v[68:69], v[30:31] op_sel_hi:[1,0]
	ds_read_b128 v[68:71], v87 offset:65344
	v_cvt_pk_bf16_f32 v88, v46, v47
	v_pk_mul_f32 v[46:47], v[66:67], v[30:31] op_sel_hi:[1,0]
	ds_read_b128 v[100:103], v86 offset:31232
	v_cvt_pk_bf16_f32 v90, v46, v47
	v_pk_mul_f32 v[46:47], v[64:65], v[30:31] op_sel_hi:[1,0]
	v_cvt_pk_bf16_f32 v65, v56, v57
	v_cvt_pk_bf16_f32 v64, v46, v47
	v_pk_mul_f32 v[46:47], v[72:73], v[30:31] op_sel_hi:[1,0]
	v_pk_mul_f32 v[56:57], v[74:75], v[30:31] op_sel_hi:[1,0]
	v_cvt_pk_bf16_f32 v66, v46, v47
	v_cvt_pk_bf16_f32 v67, v56, v57
	ds_read_b128 v[72:75], v86 offset:15680
	v_pk_mul_f32 v[46:47], v[48:49], v[30:31] op_sel_hi:[1,0]
	v_pk_mul_f32 v[48:49], v[58:59], v[30:31] op_sel_hi:[1,0]
	ds_read_b128 v[56:59], v87 offset:65408
	s_waitcnt lgkmcnt(5)
	v_mfma_f32_16x16x32_bf16 v[92:95], v[92:95], v[88:91], 0
	ds_read_b128 v[104:107], v86 offset:46848
	v_pk_mul_f32 v[44:45], v[44:45], v[30:31] op_sel_hi:[1,0]
	v_pk_mul_f32 v[26:27], v[26:27], v[30:31] op_sel_hi:[1,0]
	s_waitcnt lgkmcnt(5)
	v_mfma_f32_16x16x32_bf16 v[96:99], v[96:99], v[88:91], 0
	v_cvt_pk_bf16_f32 v44, v44, v45
	v_cvt_pk_bf16_f32 v45, v46, v47
	v_pk_mul_f32 v[46:47], v[52:53], v[30:31] op_sel_hi:[1,0]
	s_waitcnt lgkmcnt(4)
	v_mfma_f32_16x16x32_bf16 v[68:71], v[68:71], v[64:67], v[92:95]
	v_cvt_pk_bf16_f32 v46, v46, v47
	v_cvt_pk_bf16_f32 v47, v48, v49
	v_pk_mul_f32 v[48:49], v[50:51], v[30:31] op_sel_hi:[1,0]
	v_pk_mul_f32 v[50:51], v[54:55], v[30:31] op_sel_hi:[1,0]
	v_cvt_pk_bf16_f32 v48, v48, v49
	v_cvt_pk_bf16_f32 v49, v50, v51
	v_pk_mul_f32 v[50:51], v[60:61], v[30:31] op_sel_hi:[1,0]
	v_pk_mul_f32 v[52:53], v[62:63], v[30:31] op_sel_hi:[1,0]
	s_waitcnt lgkmcnt(2)
	v_mfma_f32_16x16x32_bf16 v[72:75], v[72:75], v[64:67], v[96:99]
	ds_read_b128 v[92:95], v86 offset:31296
	v_cvt_pk_bf16_f32 v50, v50, v51
	v_cvt_pk_bf16_f32 v51, v52, v53
	ds_read_b128 v[96:99], v86 offset:46912
	ds_read_b128 v[52:55], v87 offset:65472
	s_waitcnt lgkmcnt(4)
	v_mfma_f32_16x16x32_bf16 v[56:59], v[56:59], v[44:47], v[68:71]
	v_mul_f32_e64 v28, v28, v30
	v_mul_f32_e64 v29, v29, v30
	v_cvt_pk_bf16_f32 v26, v26, v27
	v_cvt_pk_bf16_f32 v27, v28, v29
	ds_read_b128 v[68:71], v86 offset:15744
	v_mfma_f32_16x16x32_bf16 v[100:103], v[100:103], v[88:91], 0
	v_mul_f32_e64 v28, v34, v30
	v_mul_f32_e64 v29, v35, v30
	v_pk_mul_f32 v[34:35], v[38:39], v[30:31] op_sel_hi:[1,0]
	v_cvt_pk_bf16_f32 v28, v28, v29
	s_waitcnt lgkmcnt(4)
	v_mfma_f32_16x16x32_bf16 v[88:91], v[104:107], v[88:91], 0
	v_cvt_pk_bf16_f32 v29, v34, v35
	v_pk_mul_f32 v[32:33], v[32:33], v[30:31] op_sel_hi:[1,0]
	v_pk_mul_f32 v[34:35], v[36:37], v[30:31] op_sel_hi:[1,0]
	s_waitcnt lgkmcnt(3)
	v_mfma_f32_16x16x32_bf16 v[92:95], v[92:95], v[64:67], v[100:103]
	v_cvt_pk_bf16_f32 v32, v32, v33
	v_cvt_pk_bf16_f32 v33, v34, v35
	v_pk_mul_f32 v[34:35], v[40:41], v[30:31] op_sel_hi:[1,0]
	s_waitcnt lgkmcnt(2)
	v_mfma_f32_16x16x32_bf16 v[64:67], v[96:99], v[64:67], v[88:91]
	v_mul_f32_e64 v36, v42, v30
	v_mul_f32_e64 v37, v43, v30
	ds_read_b128 v[60:63], v86 offset:31424
	v_cvt_pk_bf16_f32 v34, v34, v35
	ds_read_b128 v[88:91], v86 offset:46976
	s_waitcnt lgkmcnt(3)
	v_mfma_f32_16x16x32_bf16 v[52:55], v[52:55], v[48:51], v[56:59]
	v_cvt_pk_bf16_f32 v35, v36, v37
	ds_read_b128 v[36:39], v86 offset:320
	v_pk_mul_f32 v[0:1], v[0:1], v[30:31] op_sel_hi:[1,0]
	ds_read_b128 v[56:59], v86 offset:15808
	s_waitcnt lgkmcnt(4)
	v_mfma_f32_16x16x32_bf16 v[68:71], v[68:71], v[44:47], v[72:75]
	v_mul_f32_e64 v2, v2, v30
	v_mul_f32_e64 v3, v3, v30
	v_cvt_pk_bf16_f32 v0, v0, v1
	v_cvt_pk_bf16_f32 v1, v2, v3
	ds_read_b128 v[72:75], v86 offset:31360
	s_waitcnt lgkmcnt(0)
	v_mfma_f32_16x16x32_bf16 v[72:75], v[72:75], v[44:47], v[92:95]
	v_mul_f32_e64 v2, v6, v30
	v_mul_f32_e64 v3, v7, v30
	v_pk_mul_f32 v[6:7], v[10:11], v[30:31] op_sel_hi:[1,0]
	v_cvt_pk_bf16_f32 v2, v2, v3
	v_mfma_f32_16x16x32_bf16 v[44:47], v[88:91], v[44:47], v[64:67]
	v_cvt_pk_bf16_f32 v3, v6, v7
	v_pk_mul_f32 v[4:5], v[4:5], v[30:31] op_sel_hi:[1,0]
	v_pk_mul_f32 v[6:7], v[8:9], v[30:31] op_sel_hi:[1,0]
	ds_read_b128 v[64:67], v86 offset:47040
	v_cvt_pk_bf16_f32 v4, v4, v5
	v_cvt_pk_bf16_f32 v5, v6, v7
	v_pk_mul_f32 v[6:7], v[22:23], v[30:31] op_sel_hi:[1,0]
	v_pk_mul_f32 v[8:9], v[24:25], v[30:31] op_sel_hi:[1,0]
	v_mfma_f32_16x16x32_bf16 v[56:59], v[56:59], v[48:51], v[68:71]
	v_cvt_pk_bf16_f32 v6, v6, v7
	v_cvt_pk_bf16_f32 v7, v8, v9
	ds_read_b128 v[8:11], v86 offset:448
	v_mfma_f32_16x16x32_bf16 v[60:63], v[60:63], v[48:51], v[72:75]
	ds_read_b128 v[40:43], v86 offset:15936
	ds_read_b128 v[22:25], v86 offset:16064
	s_waitcnt lgkmcnt(3)
	v_mfma_f32_16x16x32_bf16 v[44:47], v[64:67], v[48:51], v[44:47]
	ds_read_b128 v[48:51], v86 offset:256
	s_waitcnt lgkmcnt(0)
	v_mfma_f32_16x16x32_bf16 v[48:51], v[48:51], v[26:29], v[52:55]
	s_nop 2
	ds_read_b128 v[52:55], v86 offset:15872
	s_waitcnt lgkmcnt(0)
	v_mfma_f32_16x16x32_bf16 v[52:55], v[52:55], v[26:29], v[56:59]
	s_nop 2
	ds_read_b128 v[56:59], v86 offset:31488
	s_waitcnt lgkmcnt(0)
	v_mfma_f32_16x16x32_bf16 v[56:59], v[56:59], v[26:29], v[60:63]
	s_nop 2
	ds_read_b128 v[60:63], v86 offset:47104
	v_mfma_f32_16x16x32_bf16 v[36:39], v[36:39], v[32:35], v[48:51]
	s_nop 2
	ds_read_b128 v[48:51], v86 offset:47168
	s_waitcnt lgkmcnt(1)
	v_mfma_f32_16x16x32_bf16 v[26:29], v[60:63], v[26:29], v[44:47]
	s_nop 2
	ds_read_b128 v[44:47], v86 offset:31552
	v_mfma_f32_16x16x32_bf16 v[40:43], v[40:43], v[32:35], v[52:55]
	s_waitcnt lgkmcnt(0)
	v_mfma_f32_16x16x32_bf16 v[44:47], v[44:47], v[32:35], v[56:59]
	v_mfma_f32_16x16x32_bf16 v[26:29], v[48:51], v[32:35], v[26:29]
	ds_read_b128 v[32:35], v86 offset:384
	s_waitcnt lgkmcnt(0)
	v_mfma_f32_16x16x32_bf16 v[32:35], v[32:35], v[0:3], v[36:39]
	s_nop 2
	ds_read_b128 v[36:39], v86 offset:16000
	s_waitcnt lgkmcnt(0)
	v_mfma_f32_16x16x32_bf16 v[36:39], v[36:39], v[0:3], v[40:43]
	s_nop 2
	ds_read_b128 v[40:43], v86 offset:31616
	s_waitcnt lgkmcnt(0)
	v_mfma_f32_16x16x32_bf16 v[40:43], v[40:43], v[0:3], v[44:47]
	s_nop 2
	ds_read_b128 v[44:47], v86 offset:47232
	v_mfma_f32_16x16x32_bf16 v[8:11], v[8:11], v[4:7], v[32:35]
	s_nop 2
	ds_read_b128 v[32:35], v86 offset:47296
	s_waitcnt lgkmcnt(1)
	v_mfma_f32_16x16x32_bf16 v[0:3], v[44:47], v[0:3], v[26:29]
	s_nop 2
	ds_read_b128 v[26:29], v86 offset:31680
	v_mfma_f32_16x16x32_bf16 v[22:25], v[22:25], v[4:7], v[36:39]
	s_waitcnt lgkmcnt(0)
	v_mfma_f32_16x16x32_bf16 v[26:29], v[26:29], v[4:7], v[40:43]
	v_mfma_f32_16x16x32_bf16 v[0:3], v[32:35], v[4:7], v[0:3]
	v_lshlrev_b64 v[4:5], 11, v[20:21]
	v_lshl_add_u64 v[4:5], s[86:87], 0, v[4:5]
	v_lshl_add_u64 v[4:5], v[18:19], 1, v[4:5]
	v_lshl_add_u64 v[18:19], v[4:5], 0, v[192:193]
	v_cvt_pk_bf16_f32 v4, v8, v9
	v_add_co_u32_e32 v8, vcc, s0, v18
	v_readlane_b32 s0, v253, 0
	v_cvt_pk_bf16_f32 v5, v10, v11
	v_cvt_pk_bf16_f32 v6, v22, v23
	v_cvt_pk_bf16_f32 v7, v24, v25
	v_addc_co_u32_e32 v9, vcc, 0, v19, vcc
	s_add_i32 s29, s29, s0
	s_add_i32 s28, s28, s0
	v_lshl_add_u64 v[20:21], v[18:19], 0, s[6:7]
	global_store_dwordx4 v[8:9], v[4:7], off offset:1024
	s_cmpk_lt_i32 s29, 0xa00
	s_nop 0
	v_cvt_pk_bf16_f32 v4, v26, v27
	v_cvt_pk_bf16_f32 v5, v28, v29
	v_cvt_pk_bf16_f32 v6, v0, v1
	v_cvt_pk_bf16_f32 v7, v2, v3
	global_store_dwordx4 v[20:21], v[4:7], off offset:64
	s_barrier
	s_cbranch_scc0 .LBB0_659
	s_branch .Lna_top

.LBB0_700:
	s_or_b64 exec, exec, s[18:19]
	s_waitcnt vmcnt(0)
	v_max3_f32 v0, v19, v28, v24
	v_max3_f32 v0, v0, v26, v25
	v_max3_f32 v0, v0, v29, v27
	v_max3_f32 v0, v0, v31, v30
	v_max3_f32 v0, v0, v33, v32
	v_max3_f32 v0, v0, v35, v34
	v_max3_f32 v0, v0, v38, v36
	v_max3_f32 v0, v0, v40, v39
	v_max3_f32 v0, v0, v43, v41
	v_max3_f32 v0, v0, v45, v44
	v_max3_f32 v0, v0, v47, v46
	v_max3_f32 v0, v0, v49, v48
	v_max3_f32 v0, v0, v51, v50
	v_max3_f32 v0, v0, v53, v52
	v_max3_f32 v0, v0, v59, v58
	v_max3_f32 v0, v0, v66, v67
	v_max3_f32 v0, v0, v95, v94
	v_max3_f32 v0, v0, v97, v96
	v_max3_f32 v0, v0, v99, v98
	v_max3_f32 v0, v0, v101, v100
	v_max3_f32 v0, v0, v103, v102
	v_max3_f32 v0, v0, v105, v104
	v_max3_f32 v0, v0, v107, v106
	v_max3_f32 v0, v0, v109, v108
	v_max3_f32 v0, v0, v111, v110
	v_max3_f32 v0, v0, v113, v112
	v_max3_f32 v0, v0, v115, v114
	v_max3_f32 v0, v0, v117, v116
	v_max3_f32 v0, v0, v119, v118
	v_max3_f32 v0, v0, v121, v120
	v_max3_f32 v0, v0, v123, v122
	v_max3_f32 v0, v0, v125, v124
	v_max3_f32 v0, v0, v127, v126
	v_add_u32_e32 v1, 64, v242
	v_max3_f32 v0, v0, v129, v128
	v_cmp_lt_i32_e32 vcc, v237, v1
	v_max3_f32 v0, v0, v6, v7
	v_max3_f32 v0, v0, v131, v130
	v_cndmask_b32_e32 v2, v220, v237, vcc
	v_lshlrev_b32_e32 v132, 2, v2
	ds_bpermute_b32 v2, v132, v0
	v_cmp_lt_i32_e32 vcc, v236, v1
	s_lshl_b32 s0, s25, 6
	s_lshl_b32 s0, s0, 1
	s_waitcnt lgkmcnt(0)
	v_max_f32_e32 v2, v2, v2
	v_cndmask_b32_e32 v1, v220, v236, vcc
	v_max_f32_e32 v0, v0, v2
	v_lshlrev_b32_e32 v134, 2, v1
	ds_bpermute_b32 v1, v134, v0
	s_xor_b64 s[18:19], s[20:21], -1
	s_mov_b32 s97, 1
	s_mov_b64 s[20:21], 0
	s_and_b64 vcc, exec, s[18:19]
	s_waitcnt lgkmcnt(0)
	v_max_f32_e32 v1, v1, v1
	v_max_f32_e32 v133, v0, v1
	v_mul_f32_e32 v147, 0xbfb8aa3b, v133
	v_fmamk_f32 v1, v24, 0x3fb8aa3b, v147
	v_exp_f32_e32 v71, v1
	v_fmamk_f32 v1, v26, 0x3fb8aa3b, v147
	v_exp_f32_e32 v78, v1
	v_fmamk_f32 v1, v25, 0x3fb8aa3b, v147
	v_exp_f32_e32 v79, v1
	v_fmamk_f32 v1, v29, 0x3fb8aa3b, v147
	v_exp_f32_e32 v82, v1
	v_fmamk_f32 v1, v27, 0x3fb8aa3b, v147
	v_exp_f32_e32 v83, v1
	v_fmamk_f32 v1, v31, 0x3fb8aa3b, v147
	v_exp_f32_e32 v84, v1
	v_fmamk_f32 v1, v30, 0x3fb8aa3b, v147
	v_exp_f32_e32 v85, v1
	v_fmamk_f32 v1, v33, 0x3fb8aa3b, v147
	v_exp_f32_e32 v64, v1
	v_fmamk_f32 v1, v32, 0x3fb8aa3b, v147
	v_exp_f32_e32 v65, v1
	v_fmamk_f32 v1, v35, 0x3fb8aa3b, v147
	v_exp_f32_e32 v72, v1
	v_fmamk_f32 v1, v34, 0x3fb8aa3b, v147
	v_exp_f32_e32 v73, v1
	v_fmamk_f32 v1, v38, 0x3fb8aa3b, v147
	v_exp_f32_e32 v76, v1
	v_fmamk_f32 v1, v36, 0x3fb8aa3b, v147
	v_exp_f32_e32 v77, v1
	v_fmamk_f32 v1, v40, 0x3fb8aa3b, v147
	v_exp_f32_e32 v80, v1
	v_fmamk_f32 v1, v39, 0x3fb8aa3b, v147
	v_exp_f32_e32 v81, v1
	v_fmamk_f32 v1, v43, 0x3fb8aa3b, v147
	v_exp_f32_e32 v56, v1
	v_fmamk_f32 v1, v41, 0x3fb8aa3b, v147
	v_exp_f32_e32 v57, v1
	v_fmamk_f32 v1, v45, 0x3fb8aa3b, v147
	v_exp_f32_e32 v62, v1
	v_fmamk_f32 v1, v44, 0x3fb8aa3b, v147
	v_exp_f32_e32 v63, v1
	v_fmamk_f32 v1, v47, 0x3fb8aa3b, v147
	v_exp_f32_e32 v68, v1
	v_fmamk_f32 v1, v46, 0x3fb8aa3b, v147
	v_exp_f32_e32 v69, v1
	v_fmamk_f32 v1, v49, 0x3fb8aa3b, v147
	v_exp_f32_e32 v74, v1
	v_fmamk_f32 v1, v48, 0x3fb8aa3b, v147
	v_exp_f32_e32 v75, v1
	v_fmamk_f32 v1, v51, 0x3fb8aa3b, v147
	v_exp_f32_e32 v48, v1
	v_fmamk_f32 v1, v50, 0x3fb8aa3b, v147
	v_exp_f32_e32 v49, v1
	v_fmamk_f32 v1, v53, 0x3fb8aa3b, v147
	v_exp_f32_e32 v54, v1
	v_fmamk_f32 v1, v52, 0x3fb8aa3b, v147
	v_exp_f32_e32 v55, v1
	v_fmamk_f32 v1, v59, 0x3fb8aa3b, v147
	v_exp_f32_e32 v60, v1
	v_fmamk_f32 v1, v58, 0x3fb8aa3b, v147
	v_exp_f32_e32 v61, v1
	v_fmamk_f32 v1, v66, 0x3fb8aa3b, v147
	v_exp_f32_e32 v66, v1
	v_fmamk_f32 v1, v67, 0x3fb8aa3b, v147
	v_fmamk_f32 v0, v28, 0x3fb8aa3b, v147
	v_exp_f32_e32 v67, v1
	v_fmamk_f32 v1, v95, 0x3fb8aa3b, v147
	v_exp_f32_e32 v70, v0
	v_exp_f32_e32 v40, v1
	v_fmamk_f32 v1, v94, 0x3fb8aa3b, v147
	v_exp_f32_e32 v41, v1
	v_fmamk_f32 v1, v97, 0x3fb8aa3b, v147
	v_add_f32_e32 v0, 0, v70
	v_add_f32_e32 v0, v71, v0
	v_exp_f32_e32 v46, v1
	v_fmamk_f32 v1, v96, 0x3fb8aa3b, v147
	v_add_f32_e32 v0, v78, v0
	v_add_f32_e32 v0, v79, v0
	v_exp_f32_e32 v47, v1
	v_fmamk_f32 v1, v99, 0x3fb8aa3b, v147
	v_add_f32_e32 v0, v82, v0
	v_add_f32_e32 v0, v83, v0
	v_exp_f32_e32 v52, v1
	v_fmamk_f32 v1, v98, 0x3fb8aa3b, v147
	v_add_f32_e32 v0, v84, v0
	v_add_f32_e32 v0, v85, v0
	v_exp_f32_e32 v53, v1
	v_fmamk_f32 v1, v101, 0x3fb8aa3b, v147
	v_add_f32_e32 v0, v64, v0
	v_add_f32_e32 v0, v65, v0
	v_exp_f32_e32 v58, v1
	v_fmamk_f32 v1, v100, 0x3fb8aa3b, v147
	v_add_f32_e32 v0, v72, v0
	v_add_f32_e32 v0, v73, v0
	v_exp_f32_e32 v59, v1
	v_fmamk_f32 v1, v103, 0x3fb8aa3b, v147
	v_add_f32_e32 v0, v76, v0
	v_add_f32_e32 v0, v77, v0
	v_exp_f32_e32 v30, v1
	v_fmamk_f32 v1, v102, 0x3fb8aa3b, v147
	v_add_f32_e32 v0, v80, v0
	v_add_f32_e32 v0, v81, v0
	v_exp_f32_e32 v31, v1
	v_fmamk_f32 v1, v105, 0x3fb8aa3b, v147
	v_add_f32_e32 v0, v56, v0
	v_add_f32_e32 v0, v57, v0
	v_exp_f32_e32 v38, v1
	v_fmamk_f32 v1, v104, 0x3fb8aa3b, v147
	v_add_f32_e32 v0, v62, v0
	v_add_f32_e32 v0, v63, v0
	v_exp_f32_e32 v39, v1
	v_fmamk_f32 v1, v107, 0x3fb8aa3b, v147
	v_add_f32_e32 v0, v68, v0
	v_add_f32_e32 v0, v69, v0
	v_exp_f32_e32 v44, v1
	v_fmamk_f32 v1, v106, 0x3fb8aa3b, v147
	v_add_f32_e32 v0, v74, v0
	v_add_f32_e32 v0, v75, v0
	v_exp_f32_e32 v45, v1
	v_fmamk_f32 v1, v109, 0x3fb8aa3b, v147
	v_add_f32_e32 v0, v48, v0
	v_add_f32_e32 v0, v49, v0
	v_exp_f32_e32 v50, v1
	v_fmamk_f32 v1, v108, 0x3fb8aa3b, v147
	v_add_f32_e32 v0, v54, v0
	v_add_f32_e32 v0, v55, v0
	v_exp_f32_e32 v51, v1
	v_fmamk_f32 v1, v111, 0x3fb8aa3b, v147
	v_add_f32_e32 v0, v60, v0
	v_add_f32_e32 v0, v61, v0
	v_exp_f32_e32 v10, v1
	v_fmamk_f32 v1, v110, 0x3fb8aa3b, v147
	v_add_f32_e32 v0, v66, v0
	v_add_f32_e32 v0, v67, v0
	v_exp_f32_e32 v11, v1
	v_fmamk_f32 v1, v113, 0x3fb8aa3b, v147
	v_add_f32_e32 v0, v40, v0
	v_add_f32_e32 v0, v41, v0
	v_exp_f32_e32 v28, v1
	v_fmamk_f32 v1, v112, 0x3fb8aa3b, v147
	v_add_f32_e32 v0, v46, v0
	v_add_f32_e32 v0, v47, v0
	v_exp_f32_e32 v29, v1
	v_fmamk_f32 v1, v115, 0x3fb8aa3b, v147
	v_add_f32_e32 v0, v52, v0
	v_add_f32_e32 v0, v53, v0
	v_exp_f32_e32 v34, v1
	v_fmamk_f32 v1, v114, 0x3fb8aa3b, v147
	v_add_f32_e32 v0, v58, v0
	v_add_f32_e32 v0, v59, v0
	v_exp_f32_e32 v35, v1
	v_fmamk_f32 v1, v117, 0x3fb8aa3b, v147
	v_add_f32_e32 v0, v30, v0
	v_add_f32_e32 v0, v31, v0
	v_exp_f32_e32 v42, v1
	v_fmamk_f32 v1, v116, 0x3fb8aa3b, v147
	v_add_f32_e32 v0, v38, v0
	v_add_f32_e32 v0, v39, v0
	v_exp_f32_e32 v43, v1
	v_fmamk_f32 v1, v119, 0x3fb8aa3b, v147
	v_add_f32_e32 v0, v44, v0
	v_add_f32_e32 v0, v45, v0
	v_exp_f32_e32 v4, v1
	v_fmamk_f32 v1, v118, 0x3fb8aa3b, v147
	v_add_f32_e32 v0, v50, v0
	v_add_f32_e32 v0, v51, v0
	v_exp_f32_e32 v5, v1
	v_fmamk_f32 v1, v121, 0x3fb8aa3b, v147
	v_add_f32_e32 v0, v10, v0
	v_add_f32_e32 v0, v11, v0
	v_exp_f32_e32 v8, v1
	v_fmamk_f32 v1, v120, 0x3fb8aa3b, v147
	v_add_f32_e32 v0, v28, v0
	v_add_f32_e32 v0, v29, v0
	v_exp_f32_e32 v9, v1
	v_fmamk_f32 v1, v123, 0x3fb8aa3b, v147
	v_add_f32_e32 v0, v34, v0
	v_add_f32_e32 v0, v35, v0
	v_exp_f32_e32 v26, v1
	v_fmamk_f32 v1, v122, 0x3fb8aa3b, v147
	v_add_f32_e32 v0, v42, v0
	v_add_f32_e32 v0, v43, v0
	v_exp_f32_e32 v27, v1
	v_fmamk_f32 v1, v125, 0x3fb8aa3b, v147
	v_add_f32_e32 v0, v4, v0
	v_add_f32_e32 v0, v5, v0
	v_exp_f32_e32 v32, v1
	v_fmamk_f32 v1, v124, 0x3fb8aa3b, v147
	v_add_f32_e32 v0, v8, v0
	v_add_f32_e32 v0, v9, v0
	v_exp_f32_e32 v33, v1
	v_add_f32_e32 v0, v26, v0
	v_add_f32_e32 v0, v27, v0
	v_add_f32_e32 v0, v32, v0
	v_add_f32_e32 v1, v33, v0
	v_fmamk_f32 v0, v127, 0x3fb8aa3b, v147
	v_exp_f32_e32 v0, v0
	v_sub_f32_e32 v6, v6, v133
	v_mul_f32_e32 v6, 0x3fb8aa3b, v6
	v_sub_f32_e32 v7, v7, v133
	v_add_f32_e32 v2, v0, v1
	v_fmamk_f32 v1, v126, 0x3fb8aa3b, v147
	v_exp_f32_e32 v1, v1
	v_exp_f32_e32 v6, v6
	v_mul_f32_e32 v7, 0x3fb8aa3b, v7
	v_exp_f32_e32 v7, v7
	v_add_f32_e32 v3, v1, v2
	v_fmamk_f32 v2, v129, 0x3fb8aa3b, v147
	v_exp_f32_e32 v2, v2
	v_sub_f32_e32 v19, v19, v133
	v_mul_f32_e32 v19, 0x3fb8aa3b, v19
	v_exp_f32_e32 v19, v19
	v_add_f32_e32 v24, v2, v3
	v_fmamk_f32 v3, v128, 0x3fb8aa3b, v147
	v_exp_f32_e32 v3, v3
	ds_read_b128 v[98:101], v15 offset:64768
	ds_read_b128 v[102:105], v86 offset:25088
	ds_read_b128 v[106:109], v86 offset:37632
	v_add_f32_e32 v24, v3, v24
	v_add_f32_e32 v24, v6, v24
	v_add_f32_e32 v25, v7, v24
	v_fmamk_f32 v24, v131, 0x3fb8aa3b, v147
	v_exp_f32_e32 v24, v24
	s_nop 0
	v_add_f32_e32 v36, v24, v25
	v_fmamk_f32 v25, v130, 0x3fb8aa3b, v147
	v_exp_f32_e32 v25, v25
	s_nop 0
	v_add_f32_e32 v36, v25, v36
	ds_bpermute_b32 v94, v132, v36
	s_waitcnt lgkmcnt(0)
	v_add_f32_e32 v36, v36, v94
	ds_bpermute_b32 v94, v134, v36
	s_waitcnt lgkmcnt(0)
	v_add_f32_e32 v36, v36, v94
	v_add_f32_e32 v19, v19, v36
	v_rcp_f32_e32 v36, v19
	s_nop 0
	v_pk_mul_f32 v[70:71], v[70:71], v[36:37] op_sel_hi:[1,0]
	v_pk_mul_f32 v[78:79], v[78:79], v[36:37] op_sel_hi:[1,0]
	v_cvt_pk_bf16_f32 v94, v70, v71
	v_cvt_pk_bf16_f32 v95, v78, v79
	v_pk_mul_f32 v[70:71], v[82:83], v[36:37] op_sel_hi:[1,0]
	v_pk_mul_f32 v[78:79], v[84:85], v[36:37] op_sel_hi:[1,0]
	ds_read_b128 v[82:85], v15 offset:52224
	v_pk_mul_f32 v[64:65], v[64:65], v[36:37] op_sel_hi:[1,0]
	v_cvt_pk_bf16_f32 v96, v70, v71
	v_pk_mul_f32 v[72:73], v[72:73], v[36:37] op_sel_hi:[1,0]
	v_cvt_pk_bf16_f32 v70, v64, v65
	v_pk_mul_f32 v[64:65], v[76:77], v[36:37] op_sel_hi:[1,0]
	v_pk_mul_f32 v[76:77], v[80:81], v[36:37] op_sel_hi:[1,0]
	v_cvt_pk_bf16_f32 v97, v78, v79
	v_cvt_pk_bf16_f32 v71, v72, v73
	v_cvt_pk_bf16_f32 v73, v76, v77
	ds_read_b128 v[76:79], v15 offset:52288
	s_waitcnt lgkmcnt(1)
	v_mfma_f32_16x16x32_bf16 v[82:85], v[82:85], v[94:97], 0
	v_cvt_pk_bf16_f32 v72, v64, v65
	v_pk_mul_f32 v[56:57], v[56:57], v[36:37] op_sel_hi:[1,0]
	v_pk_mul_f32 v[64:65], v[62:63], v[36:37] op_sel_hi:[1,0]
	s_waitcnt lgkmcnt(0)
	v_mfma_f32_16x16x32_bf16 v[76:79], v[76:79], v[70:73], v[82:85]
	s_nop 2
	ds_read_b128 v[80:83], v15 offset:64832
	v_cvt_pk_bf16_f32 v62, v56, v57
	v_pk_mul_f32 v[56:57], v[68:69], v[36:37] op_sel_hi:[1,0]
	v_mfma_f32_16x16x32_bf16 v[98:101], v[98:101], v[94:97], 0
	v_mul_f32_e64 v68, v74, v36
	v_mul_f32_e64 v69, v75, v36
	v_cvt_pk_bf16_f32 v63, v64, v65
	v_cvt_pk_bf16_f32 v64, v56, v57
	s_waitcnt lgkmcnt(0)
	v_mfma_f32_16x16x32_bf16 v[80:83], v[80:83], v[70:73], v[98:101]
	v_cvt_pk_bf16_f32 v65, v68, v69
	s_nop 1
	ds_read_b128 v[98:101], v86 offset:25152
	v_pk_mul_f32 v[48:49], v[48:49], v[36:37] op_sel_hi:[1,0]
	v_mfma_f32_16x16x32_bf16 v[102:105], v[102:105], v[94:97], 0
	v_mul_f32_e64 v56, v54, v36
	v_mul_f32_e64 v57, v55, v36
	v_cvt_pk_bf16_f32 v54, v48, v49
	v_pk_mul_f32 v[48:49], v[60:61], v[36:37] op_sel_hi:[1,0]
	s_waitcnt lgkmcnt(0)
	v_mfma_f32_16x16x32_bf16 v[98:101], v[98:101], v[70:73], v[102:105]
	v_mul_f32_e64 v60, v66, v36
	v_mul_f32_e64 v61, v67, v36
	s_nop 0
	ds_read_b128 v[102:105], v86 offset:37696
	v_mfma_f32_16x16x32_bf16 v[94:97], v[106:109], v[94:97], 0
	v_cvt_pk_bf16_f32 v55, v56, v57
	v_cvt_pk_bf16_f32 v56, v48, v49
	v_cvt_pk_bf16_f32 v57, v60, v61
	s_waitcnt lgkmcnt(0)
	v_mfma_f32_16x16x32_bf16 v[70:73], v[102:105], v[70:73], v[94:97]
	v_mul_f32_e64 v40, v40, v36
	v_mul_f32_e64 v41, v41, v36
	s_nop 0
	ds_read_b128 v[94:97], v15 offset:52352
	v_pk_mul_f32 v[48:49], v[46:47], v[36:37] op_sel_hi:[1,0]
	s_waitcnt lgkmcnt(0)
	v_mfma_f32_16x16x32_bf16 v[74:77], v[94:97], v[62:65], v[76:79]
	ds_read_b128 v[94:97], v15 offset:64896
	v_cvt_pk_bf16_f32 v46, v40, v41
	v_pk_mul_f32 v[40:41], v[52:53], v[36:37] op_sel_hi:[1,0]
	s_waitcnt lgkmcnt(0)
	v_mfma_f32_16x16x32_bf16 v[78:81], v[94:97], v[62:65], v[80:83]
	s_nop 2
	ds_read_b128 v[82:85], v86 offset:25216
	ds_read_b128 v[94:97], v86 offset:37760
	s_waitcnt lgkmcnt(1)
	v_mfma_f32_16x16x32_bf16 v[82:85], v[82:85], v[62:65], v[98:101]
	ds_read_b128 v[66:69], v15 offset:52416
	v_pk_mul_f32 v[52:53], v[58:59], v[36:37] op_sel_hi:[1,0]
	v_cvt_pk_bf16_f32 v47, v48, v49
	s_waitcnt lgkmcnt(1)
	v_mfma_f32_16x16x32_bf16 v[62:65], v[94:97], v[62:65], v[70:73]
	v_cvt_pk_bf16_f32 v48, v40, v41
	v_cvt_pk_bf16_f32 v49, v52, v53
	v_pk_mul_f32 v[30:31], v[30:31], v[36:37] op_sel_hi:[1,0]
	ds_read_b128 v[70:73], v15 offset:64960
	s_waitcnt lgkmcnt(1)
	v_mfma_f32_16x16x32_bf16 v[66:69], v[66:69], v[54:57], v[74:77]
	v_mul_f32_e64 v40, v38, v36
	v_mul_f32_e64 v41, v39, v36
	v_cvt_pk_bf16_f32 v38, v30, v31
	ds_read_b128 v[74:77], v86 offset:25280
	s_waitcnt lgkmcnt(1)
	v_mfma_f32_16x16x32_bf16 v[70:73], v[70:73], v[54:57], v[78:81]
	s_nop 2
	ds_read_b128 v[78:81], v86 offset:37824
	ds_read_b128 v[58:61], v15 offset:52480
	s_waitcnt lgkmcnt(2)
	v_mfma_f32_16x16x32_bf16 v[74:77], v[74:77], v[54:57], v[82:85]
	v_mul_f32_e64 v30, v44, v36
	v_mul_f32_e64 v31, v45, v36
	v_pk_mul_f32 v[44:45], v[50:51], v[36:37] op_sel_hi:[1,0]
	v_cvt_pk_bf16_f32 v39, v40, v41
	s_waitcnt lgkmcnt(1)
	v_mfma_f32_16x16x32_bf16 v[54:57], v[78:81], v[54:57], v[62:65]
	v_cvt_pk_bf16_f32 v40, v30, v31
	v_cvt_pk_bf16_f32 v41, v44, v45
	s_nop 0
	ds_read_b128 v[62:65], v15 offset:65024
	s_waitcnt lgkmcnt(1)
	v_mfma_f32_16x16x32_bf16 v[58:61], v[58:61], v[46:49], v[66:69]
	v_mul_f32_e64 v10, v10, v36
	v_mul_f32_e64 v11, v11, v36
	v_pk_mul_f32 v[30:31], v[28:29], v[36:37] op_sel_hi:[1,0]
	v_cvt_pk_bf16_f32 v28, v10, v11
	s_waitcnt lgkmcnt(0)
	v_mfma_f32_16x16x32_bf16 v[62:65], v[62:65], v[46:49], v[70:73]
	ds_read_b128 v[66:69], v86 offset:25344
	s_nop 1
	ds_read_b128 v[70:73], v86 offset:37888
	s_waitcnt lgkmcnt(1)
	v_mfma_f32_16x16x32_bf16 v[66:69], v[66:69], v[46:49], v[74:77]
	ds_read_b128 v[50:53], v15 offset:52544
	v_pk_mul_f32 v[10:11], v[34:35], v[36:37] op_sel_hi:[1,0]
	v_pk_mul_f32 v[34:35], v[42:43], v[36:37] op_sel_hi:[1,0]
	s_waitcnt lgkmcnt(1)
	v_mfma_f32_16x16x32_bf16 v[46:49], v[70:73], v[46:49], v[54:57]
	v_cvt_pk_bf16_f32 v29, v30, v31
	v_cvt_pk_bf16_f32 v30, v10, v11
	v_cvt_pk_bf16_f32 v31, v34, v35
	ds_read_b128 v[54:57], v15 offset:65088
	s_waitcnt lgkmcnt(1)
	v_mfma_f32_16x16x32_bf16 v[50:53], v[50:53], v[38:41], v[58:61]
	v_mul_f32_e64 v4, v4, v36
	v_mul_f32_e64 v5, v5, v36
	v_pk_mul_f32 v[10:11], v[8:9], v[36:37] op_sel_hi:[1,0]
	ds_read_b128 v[58:61], v86 offset:25408
	s_waitcnt lgkmcnt(1)
	v_mfma_f32_16x16x32_bf16 v[54:57], v[54:57], v[38:41], v[62:65]
	s_nop 2
	ds_read_b128 v[62:65], v86 offset:37952
	ds_read_b128 v[42:45], v15 offset:52608
	s_waitcnt lgkmcnt(2)
	v_mfma_f32_16x16x32_bf16 v[58:61], v[58:61], v[38:41], v[66:69]
	v_cvt_pk_bf16_f32 v8, v4, v5
	v_pk_mul_f32 v[4:5], v[26:27], v[36:37] op_sel_hi:[1,0]
	v_pk_mul_f32 v[26:27], v[32:33], v[36:37] op_sel_hi:[1,0]
	s_waitcnt lgkmcnt(1)
	v_mfma_f32_16x16x32_bf16 v[38:41], v[62:65], v[38:41], v[46:49]
	v_cvt_pk_bf16_f32 v9, v10, v11
	v_cvt_pk_bf16_f32 v10, v4, v5
	s_nop 0
	ds_read_b128 v[46:49], v15 offset:65152
	s_waitcnt lgkmcnt(1)
	v_mfma_f32_16x16x32_bf16 v[42:45], v[42:45], v[28:31], v[50:53]
	v_cvt_pk_bf16_f32 v11, v26, v27
	v_pk_mul_f32 v[0:1], v[0:1], v[36:37] op_sel_hi:[1,0]
	v_pk_mul_f32 v[2:3], v[2:3], v[36:37] op_sel_hi:[1,0]
	s_waitcnt lgkmcnt(0)
	v_mfma_f32_16x16x32_bf16 v[46:49], v[46:49], v[28:31], v[54:57]
	ds_read_b128 v[50:53], v86 offset:25472
	s_nop 1
	ds_read_b128 v[54:57], v86 offset:38016
	s_waitcnt lgkmcnt(1)
	v_mfma_f32_16x16x32_bf16 v[50:53], v[50:53], v[28:31], v[58:61]
	ds_read_b128 v[32:35], v15 offset:52672
	v_cvt_pk_bf16_f32 v0, v0, v1
	v_cvt_pk_bf16_f32 v1, v2, v3
	s_waitcnt lgkmcnt(1)
	v_mfma_f32_16x16x32_bf16 v[28:31], v[54:57], v[28:31], v[38:41]
	v_mul_f32_e64 v2, v6, v36
	v_mul_f32_e64 v3, v7, v36
	v_pk_mul_f32 v[4:5], v[24:25], v[36:37] op_sel_hi:[1,0]
	v_cvt_pk_bf16_f32 v2, v2, v3
	ds_read_b128 v[38:41], v15 offset:65216
	s_waitcnt lgkmcnt(1)
	v_mfma_f32_16x16x32_bf16 v[32:35], v[32:35], v[8:11], v[42:45]
	v_cvt_pk_bf16_f32 v3, v4, v5
	s_nop 1
	ds_read_b128 v[42:45], v86 offset:25536
	s_waitcnt lgkmcnt(1)
	v_mfma_f32_16x16x32_bf16 v[38:41], v[38:41], v[8:11], v[46:49]
	s_nop 2
	ds_read_b128 v[46:49], v86 offset:38080
	ds_read_b128 v[4:7], v15 offset:52736
	ds_read_b128 v[24:27], v15 offset:65280
	s_waitcnt lgkmcnt(3)
	v_mfma_f32_16x16x32_bf16 v[42:45], v[42:45], v[8:11], v[50:53]
	s_waitcnt lgkmcnt(2)
	v_mfma_f32_16x16x32_bf16 v[8:11], v[46:49], v[8:11], v[28:31]
	s_nop 2
	ds_read_b128 v[28:31], v86 offset:25600
	s_waitcnt lgkmcnt(2)
	v_mfma_f32_16x16x32_bf16 v[4:7], v[4:7], v[0:3], v[32:35]
	s_nop 2
	ds_read_b128 v[32:35], v86 offset:38144
	s_waitcnt lgkmcnt(2)
	v_mfma_f32_16x16x32_bf16 v[24:27], v[24:27], v[0:3], v[38:41]
	s_nop 1
	v_cvt_pk_bf16_f32 v4, v4, v5
	v_cvt_pk_bf16_f32 v5, v6, v7
	s_waitcnt lgkmcnt(1)
	v_mfma_f32_16x16x32_bf16 v[28:31], v[28:31], v[0:3], v[42:45]
	s_waitcnt lgkmcnt(0)
	v_mfma_f32_16x16x32_bf16 v[0:3], v[32:35], v[0:3], v[8:11]
	v_cvt_pk_bf16_f32 v6, v24, v25
	v_cvt_pk_bf16_f32 v7, v26, v27
	s_nop 0
	v_lshl_add_u64 v[8:9], v[22:23], 0, s[0:1]
	global_store_dwordx4 v[8:9], v[4:7], off
	s_nop 1
	v_cvt_pk_bf16_f32 v4, v28, v29
	v_cvt_pk_bf16_f32 v5, v30, v31
	v_cvt_pk_bf16_f32 v6, v0, v1
	v_cvt_pk_bf16_f32 v7, v2, v3
	global_store_dwordx4 v[8:9], v[4:7], off offset:64
	s_cbranch_vccnz .LBB0_679
